# attention loop: branch-free SGPR-base K/V tile prefetch for prompt items (sample items keep the original per-row ladder)
# speedup vs baseline: 1.0041x; 1.0041x over previous
; __device__ __forceinline__ void item_attn(const Params& p, int l, int aidx) {
;     ...
;   const bool wave_has_rows = (32 * wid) < nq;
;   f32x4 oacc[4][2];
; #pragma unroll
;   for (int md = 0; md < 4; ++md)
; #pragma unroll
;     for (int n = 0; n < 2; ++n) oacc[md][n] = f32x4{0.f, 0.f, 0.f, 0.f};
;   float carry[2] = {1.f, 1.f};
;   const int wave_qmax = qpos0 + 32 * wid + 31;
;   float4 kreg[2][2]; float vreg[2][8];
.LBB0_625:
	global_load_dword v126, v102, s[0:1]
	s_cmp_ge_i32 s21, s47
	s_cselect_b64 s[0:1], -1, 0
	s_lshl_b32 s2, s48, 1
	s_addk_i32 s2, 0x100
	v_bfe_u32 v32, v32, 4, 2
	v_mov_b32_e32 v38, s2
	s_movk_i32 s2, 0x90
	v_mad_u32_u24 v115, v35, s2, v38
	v_xor_b32_e32 v35, 1, v32
	v_cmp_gt_u32_e64 s[14:15], v35, v32
	v_xor_b32_e32 v35, 2, v32
	v_lshlrev_b32_e32 v36, 3, v32
	v_or_b32_e32 v37, s20, v33
	v_cmp_gt_u32_e64 s[16:17], v35, v32
	v_xor_b32_e32 v35, 3, v32
	s_add_i32 s52, s18, -1
	v_lshl_add_u32 v34, v34, 1, v216
	v_lshlrev_b32_e32 v114, 2, v32
	v_cmp_gt_u32_e64 s[18:19], v35, v32
	v_add_u32_e32 v85, s21, v37
	v_mul_lo_u32 v32, v87, s2
	v_mul_lo_u32 v35, v89, s2
	v_mul_u32_u24_e32 v33, 0x90, v33
	v_lshlrev_b32_e32 v37, 1, v36
	s_movk_i32 s2, 0x100
	v_mov_b32_e32 v60, v191
	v_mov_b32_e32 v61, v191
	s_add_i32 s50, s20, s21
	v_add3_u32 v118, s2, v33, v37
	v_sub_u32_e32 v119, 0, v36
	v_mov_b32_e32 v199, v198
	v_mov_b32_e32 v62, v191
	v_mov_b32_e32 v63, v191
	v_add_u32_e32 v120, v34, v32
	v_add_u32_e32 v121, v34, v35
	v_mov_b64_e32 v[44:45], v[60:61]
	v_mov_b64_e32 v[56:57], v[60:61]
	v_mov_b64_e32 v[36:37], v[60:61]
	v_mov_b64_e32 v[52:53], v[60:61]
	v_mov_b64_e32 v[40:41], v[60:61]
	v_mov_b64_e32 v[48:49], v[60:61]
	v_mov_b64_e32 v[32:33], v[60:61]
	s_or_b32 s51, s50, 31
	v_add_u32_e32 v88, s20, v86
	v_sub_u32_e32 v116, 0x40f, v87
	v_sub_u32_e32 v117, 0x40f, v89
	v_mov_b64_e32 v[46:47], v[62:63]
	v_mov_b64_e32 v[58:59], v[62:63]
	v_mov_b64_e32 v[38:39], v[62:63]
	v_mov_b64_e32 v[54:55], v[62:63]
	v_mov_b64_e32 v[42:43], v[62:63]
	v_mov_b64_e32 v[50:51], v[62:63]
	v_mov_b64_e32 v[34:35], v[62:63]
	v_mov_b64_e32 v[90:91], v[198:199]
	v_lshl_add_u32 v229, v87, 11, v190
	v_lshl_add_u32 v230, v89, 11, v190
	s_branch .LBB0_629

; __device__ __forceinline__ unsigned pack2(float a, float b) { unsigned r; asm volatile("v_cvt_pk_bf16_f32 %0, %1, %2" : "=v"(r) : "v"(a), "v"(b)); return r; }
; __device__ __forceinline__ void item_attn(const Params& p, int l, int aidx) {
;     ...
;     {
;       if (samp) {
; #pragma unroll
;         for (int i = 0; i < 8; ++i) if (kt * 64 + 8 * wid + i >= 1040) vreg[hs][i] = 0.f;
;       }
;       uint4 v4; v4.x = pack2(vreg[hs][0], vreg[hs][1]); v4.y = pack2(vreg[hs][2], vreg[hs][3]); v4.z = pack2(vreg[hs][4], vreg[hs][5]); v4.w = pack2(vreg[hs][6], vreg[hs][7]);
;       *reinterpret_cast<uint4*>(VT + lane * 72 + 8 * wid) = v4;
;     }
;     __syncthreads();
;     if (kt > 1) ATT_LOAD_TILE(kt - 2, hs);
.LBB0_631:
	s_cmp_lt_u32 s52, 2
	v_cvt_pk_bf16_f32 v64, v103, v104
	v_cvt_pk_bf16_f32 v65, v105, v106
	v_cvt_pk_bf16_f32 v66, v107, v108
	v_cvt_pk_bf16_f32 v67, v110, v113
	ds_write_b128 v115, v[64:67] offset:9216
	s_waitcnt lgkmcnt(0)
	s_barrier
	s_cbranch_scc1 .LBB0_687
	s_and_b64 vcc, exec, s[12:13]
	s_cbranch_vccnz .Lkvfast_1
	v_add_u32_e32 v16, s49, v87
	s_and_b64 vcc, exec, s[12:13]
	v_subrev_u32_e32 v16, 64, v16
	s_cbranch_vccnz .LBB0_638
	v_min_i32_e32 v18, 0x40f, v16
	v_cmp_lt_i32_e32 vcc, s90, v16
	v_ashrrev_i32_e32 v19, 31, v18
	s_and_saveexec_b64 s[2:3], vcc
	s_xor_b64 s[4:5], exec, s[2:3]
	v_lshlrev_b64 v[16:17], 11, v[18:19]
	s_mov_b32 s2, 0xffe00000
	v_lshl_add_u64 v[16:17], s[36:37], 0, v[16:17]
	s_mov_b32 s3, -1
	v_lshl_add_u64 v[16:17], v[16:17], 0, s[2:3]
	s_andn2_saveexec_b64 s[4:5], s[4:5]
	v_lshlrev_b64 v[16:17], 11, v[18:19]
	v_lshl_add_u64 v[16:17], s[40:41], 0, v[16:17]
	s_or_b64 exec, exec, s[4:5]
	s_branch .LBB0_639
.Lkvfast_1:
	s_add_i32 s2, s49, 0xffffffc0
	s_ashr_i32 s3, s2, 31
	s_lshl_b64 s[100:101], s[2:3], 11
	s_add_u32 s100, s36, s100
	s_addc_u32 s101, s37, s101
	s_add_i32 s25, s48, s49
	global_load_dwordx4 v[16:19], v229, s[100:101]
	global_load_dwordx4 v[20:23], v230, s[100:101]
	s_add_i32 s2, s25, 0xffffffc0
	s_ashr_i32 s3, s2, 31
	s_lshl_b64 s[4:5], s[2:3], 11
	s_add_u32 s4, s38, s4
	s_addc_u32 s5, s39, s5
	global_load_dword v103, v102, s[4:5]
	global_load_dword v104, v102, s[4:5] offset:2048
	s_add_u32 s4, s4, 0x1000
	s_addc_u32 s5, s5, 0
	global_load_dword v105, v102, s[4:5]
	global_load_dword v106, v102, s[4:5] offset:2048
	s_add_u32 s4, s4, 0x1000
	s_addc_u32 s5, s5, 0
	global_load_dword v107, v102, s[4:5]
	global_load_dword v108, v102, s[4:5] offset:2048
	s_add_u32 s4, s4, 0x1000
	s_addc_u32 s5, s5, 0
	global_load_dword v110, v102, s[4:5]
	global_load_dword v113, v102, s[4:5] offset:2048
	s_add_u32 s4, s4, 0x800
	s_addc_u32 s5, s5, 0
	s_add_i32 s2, s25, 0xffffffc7
	s_ashr_i32 s3, s2, 31
	s_branch .LBB0_687

; __device__ __forceinline__ unsigned pack2(float a, float b) { unsigned r; asm volatile("v_cvt_pk_bf16_f32 %0, %1, %2" : "=v"(r) : "v"(a), "v"(b)); return r; }
; __device__ __forceinline__ void item_attn(const Params& p, int l, int aidx) {
;     ...
;     {
;       if (samp) {
; #pragma unroll
;         for (int i = 0; i < 8; ++i) if (kt * 64 + 8 * wid + i >= 1040) vreg[hs][i] = 0.f;
;       }
;       uint4 v4; v4.x = pack2(vreg[hs][0], vreg[hs][1]); v4.y = pack2(vreg[hs][2], vreg[hs][3]); v4.z = pack2(vreg[hs][4], vreg[hs][5]); v4.w = pack2(vreg[hs][6], vreg[hs][7]);
;       *reinterpret_cast<uint4*>(VT + lane * 72 + 8 * wid) = v4;
;     }
;     __syncthreads();
;     if (kt > 1) ATT_LOAD_TILE(kt - 2, hs);
.LBB0_704:
	s_cmp_lt_u32 s52, 3
	v_cvt_pk_bf16_f32 v64, v109, v111
	v_cvt_pk_bf16_f32 v65, v112, v122
	v_cvt_pk_bf16_f32 v66, v123, v124
	v_cvt_pk_bf16_f32 v67, v125, v126
	ds_write_b128 v115, v[64:67] offset:9216
	s_waitcnt lgkmcnt(0)
	s_barrier
	s_cbranch_scc1 .Lattn_touch
	s_and_b64 vcc, exec, s[12:13]
	s_cbranch_vccnz .Lkvfast_2
	v_add_u32_e32 v24, s49, v87
	s_and_b64 vcc, exec, s[12:13]
	v_add_u32_e32 v24, 0xffffff80, v24
	s_cbranch_vccnz .LBB0_711
	v_min_i32_e32 v26, 0x40f, v24
	v_cmp_lt_i32_e32 vcc, s90, v24
	v_ashrrev_i32_e32 v27, 31, v26
	s_and_saveexec_b64 s[0:1], vcc
	s_xor_b64 s[0:1], exec, s[0:1]
	v_lshlrev_b64 v[24:25], 11, v[26:27]
	s_mov_b32 s2, 0xffe00000
	v_lshl_add_u64 v[24:25], s[36:37], 0, v[24:25]
	s_mov_b32 s3, -1
	v_lshl_add_u64 v[24:25], v[24:25], 0, s[2:3]
	s_andn2_saveexec_b64 s[0:1], s[0:1]
	v_lshlrev_b64 v[24:25], 11, v[26:27]
	v_lshl_add_u64 v[24:25], s[40:41], 0, v[24:25]
	s_or_b64 exec, exec, s[0:1]
	s_branch .LBB0_712

.Lkvfast_2:
	s_add_i32 s2, s49, 0xffffff80
	s_ashr_i32 s3, s2, 31
	s_lshl_b64 s[100:101], s[2:3], 11
	s_add_u32 s100, s36, s100
	s_addc_u32 s101, s37, s101
	s_add_i32 s26, s48, s49
	global_load_dwordx4 v[24:27], v229, s[100:101]
	global_load_dwordx4 v[28:31], v230, s[100:101]
	s_add_i32 s2, s26, 0xffffff80
	s_ashr_i32 s3, s2, 31
	s_lshl_b64 s[0:1], s[2:3], 11
	s_add_u32 s0, s38, s0
	s_addc_u32 s1, s39, s1
	global_load_dword v109, v102, s[0:1]
	global_load_dword v111, v102, s[0:1] offset:2048
	s_add_u32 s0, s0, 0x1000
	s_addc_u32 s1, s1, 0
	global_load_dword v112, v102, s[0:1]
	global_load_dword v122, v102, s[0:1] offset:2048
	s_add_u32 s0, s0, 0x1000
	s_addc_u32 s1, s1, 0
	global_load_dword v123, v102, s[0:1]
	global_load_dword v124, v102, s[0:1] offset:2048
	s_add_u32 s0, s0, 0x1000
	s_addc_u32 s1, s1, 0
	global_load_dword v125, v102, s[0:1]
	global_load_dword v126, v102, s[0:1] offset:2048
	s_add_u32 s0, s0, 0x800
	s_addc_u32 s1, s1, 0
	s_add_i32 s2, s26, 0xffffff87
	s_ashr_i32 s3, s2, 31
	s_branch .LBB0_760
